# ssd3 phase: static s_setprio 1 for waves 4-7
# baseline (speedup 1.0000x reference)
.LBB0_27:
	s_andn2_b64 vcc, exec, s[0:1]
	s_cbranch_vccnz .LBB0_158
	s_cmp_gt_i32 s58, 10
	s_mov_b64 s[0:1], -1
	s_cbranch_scc0 .LBB0_132
	v_writelane_b32 v255, s0, 4
	s_nop 1
	v_writelane_b32 v255, s1, 5
	s_mov_b64 s[0:1], 0
	v_writelane_b32 v255, s0, 2
	s_nop 1
	v_writelane_b32 v255, s1, 3
	v_writelane_b32 v255, s58, 6
	s_nop 1
	v_writelane_b32 v255, s59, 7
	v_readfirstlane_b32 s66, v179
	s_cmp_ge_u32 s66, 0x100
	s_cbranch_scc0 .Lp11_np
	s_setprio 1
.Lp11_np:
	s_branch .LBB0_32
.LBB0_30:
	v_readlane_b32 s58, v255, 6
	v_readlane_b32 s59, v255, 7
	v_readlane_b32 s35, v255, 1

.LBB0_131:
	s_setprio 0
	s_mov_b64 s[0:1], 0
